# speedup vs baseline: 1.0017x; 1.0017x over previous
; __device__ __forceinline__ float softplusf_(float v) { return fmaxf(v, 0.f) + __logf(1.f + __expf(-fabsf(v))); }
; __device__ void attn_item(const Params& p, int item, u16* O) {
;     ...
;       f32x4 s[4];
;       __builtin_amdgcn_s_setprio(1);
; #pragma unroll
;       for (int mf = 0; mf < 4; ++mf) {
;         s[mf] = f32x4{0.f, 0.f, 0.f, 0.f};
; #pragma unroll
;         for (int ks = 0; ks < 4; ++ks) {
;           bf16x8 a = *(const bf16x8*)(Ks + (mf * 16 + fr) * 136 + ks * 32 + g4 * 8);
;           s[mf] = __builtin_amdgcn_mfma_f32_16x16x32_bf16(a, qf[ks], s[mf], 0, 0, 0);
;         }
;       }
;       __builtin_amdgcn_s_setprio(0);
;       float c[4][4], T[4];
;       bool valid[4][4];
; #pragma unroll
;       for (int mf = 0; mf < 4; ++mf) {
; #pragma unroll
;         for (int r = 0; r < 4; ++r) {
;           int kk = kt * 64 + mf * 16 + g4 * 4 + r;
;           valid[mf][r] = kk < qrow;
;           c[mf][r] = valid[mf][r] ? -softplusf_(s[mf][r]) : 0.f;
.LBB0_746:
	s_waitcnt lgkmcnt(0)
	s_barrier
	v_cmp_le_i32_e32 vcc, s0, v108
	s_and_saveexec_b64 s[70:71], vcc
	s_cbranch_execz .LBB0_780
	s_setprio 1
	ds_read_b128 v[64:67], v118
	ds_read_b128 v[68:71], v118 offset:64
	ds_read_b128 v[72:75], v118 offset:4352
	ds_read_b128 v[96:99], v118 offset:4416
	ds_read_b128 v[76:79], v118 offset:128
	ds_read_b128 v[100:103], v118 offset:13184
	s_waitcnt lgkmcnt(5)
	v_mfma_f32_16x16x32_bf16 v[64:67], v[64:67], v[0:3], 0
	s_waitcnt lgkmcnt(4)
	v_mfma_f32_16x16x32_bf16 v[64:67], v[68:71], v[4:7], v[64:67]
	ds_read_b128 v[68:71], v118 offset:192
	s_waitcnt lgkmcnt(2)
	v_mfma_f32_16x16x32_bf16 v[64:67], v[76:79], v[8:11], v[64:67]
	v_mfma_f32_16x16x32_bf16 v[72:75], v[72:75], v[0:3], 0
	s_waitcnt lgkmcnt(0)
	v_mfma_f32_16x16x32_bf16 v[76:79], v[68:71], v[12:15], v[64:67]
	s_nop 4
	ds_read_b128 v[64:67], v118 offset:4480
	v_mfma_f32_16x16x32_bf16 v[68:71], v[96:99], v[4:7], v[72:75]
	ds_read_b128 v[96:99], v118 offset:8832
	s_nop 1
	ds_read_b128 v[72:75], v118 offset:4544
	s_waitcnt lgkmcnt(2)
	v_mfma_f32_16x16x32_bf16 v[64:67], v[64:67], v[8:11], v[68:71]
	s_nop 2
	ds_read_b128 v[68:71], v118 offset:8704
	s_waitcnt lgkmcnt(1)
	v_mfma_f32_16x16x32_bf16 v[72:75], v[72:75], v[12:15], v[64:67]
	s_nop 2
	ds_read_b128 v[64:67], v118 offset:8768
	s_waitcnt lgkmcnt(1)
	v_mfma_f32_16x16x32_bf16 v[68:71], v[68:71], v[0:3], 0
	s_waitcnt lgkmcnt(0)
	v_mfma_f32_16x16x32_bf16 v[64:67], v[64:67], v[4:7], v[68:71]
	s_nop 5
	ds_read_b128 v[68:71], v118 offset:8896
	v_mfma_f32_16x16x32_bf16 v[64:67], v[96:99], v[8:11], v[64:67]
	ds_read_b128 v[96:99], v118 offset:13056
	s_waitcnt lgkmcnt(1)
	v_mfma_f32_16x16x32_bf16 v[68:71], v[68:71], v[12:15], v[64:67]
	s_nop 4
	ds_read_b128 v[64:67], v118 offset:13120
	s_waitcnt lgkmcnt(1)
	v_mfma_f32_16x16x32_bf16 v[96:99], v[96:99], v[0:3], 0
	s_waitcnt lgkmcnt(0)
	v_mfma_f32_16x16x32_bf16 v[64:67], v[64:67], v[4:7], v[96:99]
	s_nop 5
	ds_read_b128 v[96:99], v118 offset:13248
	v_mfma_f32_16x16x32_bf16 v[64:67], v[100:103], v[8:11], v[64:67]
	s_waitcnt lgkmcnt(0)
	v_mfma_f32_16x16x32_bf16 v[64:67], v[96:99], v[12:15], v[64:67]
	s_setprio 0
	v_or_b32_e32 v101, s0, v109
	v_cmp_lt_i32_e32 vcc, v101, v82
	v_mov_b32_e32 v97, 0
	v_mov_b32_e32 v80, 0
	v_or_b32_e32 v96, 1, v101
	v_cmp_lt_i32_e64 s[12:13], v96, v82
	v_mov_b32_e32 v99, 0
	v_or_b32_e32 v96, 2, v101
	v_cmp_lt_i32_e64 s[14:15], v96, v82
	v_or_b32_e32 v96, 3, v101
	v_cmp_lt_i32_e64 s[16:17], v96, v82
	v_mov_b32_e32 v103, 0
	v_mov_b32_e32 v96, 0
	v_or_b32_e32 v98, 16, v101
	v_cmp_lt_i32_e64 s[18:19], v98, v82
	v_or_b32_e32 v98, 17, v101
	v_cmp_lt_i32_e64 s[20:21], v98, v82
	v_mov_b32_e32 v121, 0
	v_mov_b32_e32 v120, 0
	v_or_b32_e32 v98, 18, v101
	v_cmp_lt_i32_e64 s[22:23], v98, v82
	v_or_b32_e32 v98, 19, v101
	v_cmp_lt_i32_e64 s[24:25], v98, v82
	v_mov_b32_e32 v122, 0
	v_mov_b32_e32 v98, 0
	v_or_b32_e32 v100, 32, v101
	v_cmp_lt_i32_e64 s[26:27], v100, v82
	v_or_b32_e32 v100, 33, v101
	v_cmp_lt_i32_e64 s[28:29], v100, v82
	v_mov_b32_e32 v124, 0
	v_mov_b32_e32 v123, 0
	v_or_b32_e32 v100, 34, v101
	v_cmp_lt_i32_e64 s[30:31], v100, v82
	v_or_b32_e32 v100, 35, v101
	v_cmp_lt_i32_e64 s[34:35], v100, v82
	v_mov_b32_e32 v125, 0
	v_mov_b32_e32 v100, 0
	v_or_b32_e32 v102, 48, v101
	v_cmp_lt_i32_e64 s[36:37], v102, v82
	v_or_b32_e32 v102, 49, v101
	v_cmp_lt_i32_e64 s[38:39], v102, v82
	v_mov_b32_e32 v127, 0
	v_mov_b32_e32 v126, 0
	v_or_b32_e32 v102, 50, v101
	v_cmp_lt_i32_e64 s[40:41], v102, v82
	v_or_b32_e32 v101, 51, v101
	v_cmp_lt_i32_e64 s[42:43], v101, v82
	v_mov_b32_e32 v102, 0
	v_mul_f32_e64 v158, |v76|, s76
	v_mul_f32_e64 v161, |v77|, s76
	v_mul_f32_e64 v164, |v78|, s76
	v_mul_f32_e64 v167, |v79|, s76
	v_mul_f32_e64 v170, |v72|, s76
	v_mul_f32_e64 v173, |v73|, s76
	v_mul_f32_e64 v176, |v74|, s76
	v_mul_f32_e64 v179, |v75|, s76
	v_mul_f32_e64 v182, |v68|, s76
	v_mul_f32_e64 v185, |v69|, s76
	v_mul_f32_e64 v188, |v70|, s76
	v_mul_f32_e64 v191, |v71|, s76
	v_mul_f32_e64 v194, |v64|, s76
	v_mul_f32_e64 v197, |v65|, s76
	v_mul_f32_e64 v200, |v66|, s76
	v_mul_f32_e64 v203, |v67|, s76
	v_exp_f32_e32 v158, v158
	v_exp_f32_e32 v161, v161
	v_exp_f32_e32 v164, v164
	v_exp_f32_e32 v167, v167
	v_exp_f32_e32 v170, v170
	v_exp_f32_e32 v173, v173
	v_exp_f32_e32 v176, v176
	v_exp_f32_e32 v179, v179
	v_exp_f32_e32 v182, v182
	v_exp_f32_e32 v185, v185
	v_exp_f32_e32 v188, v188
	v_exp_f32_e32 v191, v191
	v_exp_f32_e32 v194, v194
	v_exp_f32_e32 v197, v197
	v_exp_f32_e32 v200, v200
	v_exp_f32_e32 v203, v203
	v_add_f32_e32 v158, 1.0, v158
	v_add_f32_e32 v161, 1.0, v161
	v_add_f32_e32 v164, 1.0, v164
	v_add_f32_e32 v167, 1.0, v167
	v_add_f32_e32 v170, 1.0, v170
	v_add_f32_e32 v173, 1.0, v173
	v_add_f32_e32 v176, 1.0, v176
	v_add_f32_e32 v179, 1.0, v179
	v_add_f32_e32 v182, 1.0, v182
	v_add_f32_e32 v185, 1.0, v185
	v_add_f32_e32 v188, 1.0, v188
	v_add_f32_e32 v191, 1.0, v191
	v_add_f32_e32 v194, 1.0, v194
	v_add_f32_e32 v197, 1.0, v197
	v_add_f32_e32 v200, 1.0, v200
	v_add_f32_e32 v203, 1.0, v203
	v_log_f32_e32 v158, v158
	v_log_f32_e32 v161, v161
	v_log_f32_e32 v164, v164
	v_log_f32_e32 v167, v167
	v_log_f32_e32 v170, v170
	v_log_f32_e32 v173, v173
	v_log_f32_e32 v176, v176
	v_log_f32_e32 v179, v179
	v_log_f32_e32 v182, v182
	v_log_f32_e32 v185, v185
	v_log_f32_e32 v188, v188
	v_log_f32_e32 v191, v191
	v_log_f32_e32 v194, v194
	v_log_f32_e32 v197, v197
	v_log_f32_e32 v200, v200
	v_log_f32_e32 v203, v203
	v_max_f32_e32 v159, v76, v76
	v_max_f32_e32 v162, v77, v77
	v_max_f32_e32 v165, v78, v78
	v_max_f32_e32 v168, v79, v79
	v_max_f32_e32 v171, v72, v72
	v_max_f32_e32 v174, v73, v73
	v_max_f32_e32 v177, v74, v74
	v_max_f32_e32 v180, v75, v75
	v_max_f32_e32 v183, v68, v68
; __device__ __forceinline__ float softplusf_(float v) { return fmaxf(v, 0.f) + __logf(1.f + __expf(-fabsf(v))); }
; __device__ void attn_item(const Params& p, int item, u16* O) {
;     ...
;         for (int r = 0; r < 4; ++r) {
;           int kk = kt * 64 + mf * 16 + g4 * 4 + r;
;           valid[mf][r] = kk < qrow;
;           c[mf][r] = valid[mf][r] ? -softplusf_(s[mf][r]) : 0.f;
;         }
;         c[mf][2] += c[mf][3];
;         c[mf][1] += c[mf][2];
;         c[mf][0] += c[mf][1];
;         T[mf] = c[mf][0];
;       }
;       float suf[4], tot[4];
; #pragma unroll
;       for (int mf = 0; mf < 4; ++mf) {
;         float a = __shfl_xor(T[mf], 16, 64);
;         float s1 = T[mf] + a;
;         float b = __shfl_xor(s1, 32, 64);
;         tot[mf] = s1 + b;
;         suf[mf] = (g4 == 0) ? a + b : (g4 == 1) ? b : (g4 == 2) ? a : 0.f;
;       }
	v_max_f32_e32 v186, v69, v69
	v_max_f32_e32 v189, v70, v70
	v_max_f32_e32 v192, v71, v71
	v_max_f32_e32 v195, v64, v64
	v_max_f32_e32 v198, v65, v65
	v_max_f32_e32 v201, v66, v66
	v_max_f32_e32 v204, v67, v67
	v_max_f32_e32 v159, 0, v159
	v_max_f32_e32 v162, 0, v162
	v_max_f32_e32 v165, 0, v165
	v_max_f32_e32 v168, 0, v168
	v_max_f32_e32 v171, 0, v171
	v_max_f32_e32 v174, 0, v174
	v_max_f32_e32 v177, 0, v177
	v_max_f32_e32 v180, 0, v180
	v_max_f32_e32 v183, 0, v183
	v_max_f32_e32 v186, 0, v186
	v_max_f32_e32 v189, 0, v189
	v_max_f32_e32 v192, 0, v192
	v_max_f32_e32 v195, 0, v195
	v_max_f32_e32 v198, 0, v198
	v_max_f32_e32 v201, 0, v201
	v_max_f32_e32 v204, 0, v204
	v_mul_f32_e32 v160, 0x3f317217, v158
	v_mul_f32_e32 v163, 0x3f317217, v161
	v_mul_f32_e32 v166, 0x3f317217, v164
	v_mul_f32_e32 v169, 0x3f317217, v167
	v_mul_f32_e32 v172, 0x3f317217, v170
	v_mul_f32_e32 v175, 0x3f317217, v173
	v_mul_f32_e32 v178, 0x3f317217, v176
	v_mul_f32_e32 v181, 0x3f317217, v179
	v_mul_f32_e32 v184, 0x3f317217, v182
	v_mul_f32_e32 v187, 0x3f317217, v185
	v_mul_f32_e32 v190, 0x3f317217, v188
	v_mul_f32_e32 v193, 0x3f317217, v191
	v_mul_f32_e32 v196, 0x3f317217, v194
	v_mul_f32_e32 v199, 0x3f317217, v197
	v_mul_f32_e32 v202, 0x3f317217, v200
	v_mul_f32_e32 v205, 0x3f317217, v203
	v_fma_f32 v160, v158, s79, -v160
	v_fma_f32 v163, v161, s79, -v163
	v_fma_f32 v166, v164, s79, -v166
	v_fma_f32 v169, v167, s79, -v169
	v_fma_f32 v172, v170, s79, -v172
	v_fma_f32 v175, v173, s79, -v175
	v_fma_f32 v178, v176, s79, -v178
	v_fma_f32 v181, v179, s79, -v181
	v_fma_f32 v184, v182, s79, -v184
	v_fma_f32 v187, v185, s79, -v187
	v_fma_f32 v190, v188, s79, -v190
	v_fma_f32 v193, v191, s79, -v193
	v_fma_f32 v196, v194, s79, -v196
	v_fma_f32 v199, v197, s79, -v199
	v_fma_f32 v202, v200, s79, -v202
	v_fma_f32 v205, v203, s79, -v205
	v_fmac_f32_e32 v160, 0x3377d1cf, v158
	v_fmac_f32_e32 v163, 0x3377d1cf, v161
	v_fmac_f32_e32 v166, 0x3377d1cf, v164
	v_fmac_f32_e32 v169, 0x3377d1cf, v167
	v_fmac_f32_e32 v172, 0x3377d1cf, v170
	v_fmac_f32_e32 v175, 0x3377d1cf, v173
	v_fmac_f32_e32 v178, 0x3377d1cf, v176
	v_fmac_f32_e32 v181, 0x3377d1cf, v179
	v_fmac_f32_e32 v184, 0x3377d1cf, v182
	v_fmac_f32_e32 v187, 0x3377d1cf, v185
	v_fmac_f32_e32 v190, 0x3377d1cf, v188
	v_fmac_f32_e32 v193, 0x3377d1cf, v191
	v_fmac_f32_e32 v196, 0x3377d1cf, v194
	v_fmac_f32_e32 v199, 0x3377d1cf, v197
	v_fmac_f32_e32 v202, 0x3377d1cf, v200
	v_fmac_f32_e32 v205, 0x3377d1cf, v203
	v_fmac_f32_e32 v160, 0x3f317217, v158
	v_fmac_f32_e32 v163, 0x3f317217, v161
	v_fmac_f32_e32 v166, 0x3f317217, v164
	v_fmac_f32_e32 v169, 0x3f317217, v167
	v_fmac_f32_e32 v172, 0x3f317217, v170
	v_fmac_f32_e32 v175, 0x3f317217, v173
	v_fmac_f32_e32 v178, 0x3f317217, v176
	v_fmac_f32_e32 v181, 0x3f317217, v179
	v_fmac_f32_e32 v184, 0x3f317217, v182
	v_fmac_f32_e32 v187, 0x3f317217, v185
	v_fmac_f32_e32 v190, 0x3f317217, v188
	v_fmac_f32_e32 v193, 0x3f317217, v191
	v_fmac_f32_e32 v196, 0x3f317217, v194
	v_fmac_f32_e32 v199, 0x3f317217, v197
	v_fmac_f32_e32 v202, 0x3f317217, v200
	v_fmac_f32_e32 v205, 0x3f317217, v203
	v_add_f32_e32 v158, v159, v160
	v_add_f32_e32 v161, v162, v163
	v_add_f32_e32 v164, v165, v166
	v_add_f32_e32 v167, v168, v169
	v_add_f32_e32 v170, v171, v172
	v_add_f32_e32 v173, v174, v175
	v_add_f32_e32 v176, v177, v178
	v_add_f32_e32 v179, v180, v181
	v_add_f32_e32 v182, v183, v184
	v_add_f32_e32 v185, v186, v187
	v_add_f32_e32 v188, v189, v190
	v_add_f32_e32 v191, v192, v193
	v_add_f32_e32 v194, v195, v196
	v_add_f32_e32 v197, v198, v199
	v_add_f32_e32 v200, v201, v202
	v_add_f32_e32 v203, v204, v205
	v_xor_b32_e32 v158, 0x80000000, v158
	v_xor_b32_e32 v161, 0x80000000, v161
	v_xor_b32_e32 v164, 0x80000000, v164
	v_xor_b32_e32 v167, 0x80000000, v167
	v_xor_b32_e32 v170, 0x80000000, v170
	v_xor_b32_e32 v173, 0x80000000, v173
	v_xor_b32_e32 v176, 0x80000000, v176
	v_xor_b32_e32 v179, 0x80000000, v179
	v_xor_b32_e32 v182, 0x80000000, v182
	v_xor_b32_e32 v185, 0x80000000, v185
	v_xor_b32_e32 v188, 0x80000000, v188
	v_xor_b32_e32 v191, 0x80000000, v191
	v_xor_b32_e32 v194, 0x80000000, v194
	v_xor_b32_e32 v197, 0x80000000, v197
	v_xor_b32_e32 v200, 0x80000000, v200
	v_xor_b32_e32 v203, 0x80000000, v203
	v_cndmask_b32_e32 v80, 0, v158, vcc
	v_cndmask_b32_e64 v99, 0, v161, s[12:13]
	v_cndmask_b32_e64 v97, 0, v164, s[14:15]
	v_cndmask_b32_e64 v96, 0, v167, s[16:17]
	v_cndmask_b32_e64 v103, 0, v170, s[18:19]
	v_cndmask_b32_e64 v120, 0, v173, s[20:21]
	v_cndmask_b32_e64 v121, 0, v176, s[22:23]
	v_cndmask_b32_e64 v98, 0, v179, s[24:25]
	v_cndmask_b32_e64 v122, 0, v182, s[26:27]
	v_cndmask_b32_e64 v123, 0, v185, s[28:29]
	v_cndmask_b32_e64 v124, 0, v188, s[30:31]
	v_cndmask_b32_e64 v100, 0, v191, s[34:35]
	v_cndmask_b32_e64 v125, 0, v194, s[36:37]
	v_cndmask_b32_e64 v126, 0, v197, s[38:39]
	v_cndmask_b32_e64 v127, 0, v200, s[40:41]
	v_cndmask_b32_e64 v102, 0, v203, s[42:43]
	v_and_b32_e32 v101, 64, v106
	v_add_f32_e32 v138, v97, v96
	v_xor_b32_e32 v97, 16, v106
	v_add_u32_e32 v101, 64, v101
	v_add_f32_e32 v139, v127, v102
	v_cmp_lt_i32_e64 s[0:1], v97, v101
	v_add_f32_e32 v140, v126, v139
	v_add_f32_e32 v141, v125, v140
	v_cndmask_b32_e64 v97, v106, v97, s[0:1]
	v_lshlrev_b32_e32 v97, 2, v97
	ds_bpermute_b32 v130, v97, v141
	v_add_f32_e32 v136, v121, v98
	v_add_f32_e32 v137, v120, v136
	v_xor_b32_e32 v120, 32, v106
	v_add_f32_e32 v134, v124, v100
	v_cmp_lt_i32_e64 s[0:1], v120, v101
	v_add_f32_e32 v135, v123, v134
	v_add_f32_e32 v122, v122, v135
	v_cndmask_b32_e64 v101, v106, v120, s[0:1]
	v_lshlrev_b32_e32 v132, 2, v101
	s_waitcnt lgkmcnt(0)
; __device__ void attn_item(const Params& p, int item, u16* O) {
;     ...
;       float suf[4], tot[4];
; #pragma unroll
;       for (int mf = 0; mf < 4; ++mf) {
;         float a = __shfl_xor(T[mf], 16, 64);
;         float s1 = T[mf] + a;
;         float b = __shfl_xor(s1, 32, 64);
;         tot[mf] = s1 + b;
;         suf[mf] = (g4 == 0) ? a + b : (g4 == 1) ? b : (g4 == 2) ? a : 0.f;
;       }
;       float run = 0.f;
; #pragma unroll
;     ...
;         suf[mf] += run;
;         run += tot[mf];
;       }
;       float pv[4][4];
; #pragma unroll
;       for (int mf = 0; mf < 4; ++mf)
; #pragma unroll
;         for (int r = 0; r < 4; ++r) {
;           float e = s[mf][r] + c[mf][r] + suf[mf] + R;
;           pv[mf][r] = valid[mf][r] ? __expf(e) : 0.f;
;         }
;       R += run;
;       bf16x8 pb[2];
; #pragma unroll
;       for (int kp = 0; kp < 2; ++kp) {
;         unsigned w0 = pack2(pv[2 * kp][0], pv[2 * kp][1]), w1 = pack2(pv[2 * kp][2], pv[2 * kp][3]);
;         unsigned w2 = pack2(pv[2 * kp + 1][0], pv[2 * kp + 1][1]), w3 = pack2(pv[2 * kp + 1][2], pv[2 * kp + 1][3]);
;         i32x4 t4 = {(int)w0, (int)w1, (int)w2, (int)w3};
;         pb[kp] = __builtin_bit_cast(bf16x8, t4);
;       }
;       __builtin_amdgcn_s_setprio(1);
; #pragma unroll
;       for (int df = 0; df < 8; ++df)
; #pragma unroll
;         for (int kp = 0; kp < 2; ++kp) {
;           const u16* vp = Vt + (df * 16 + fr) * 72 + kp * 32 + g4 * 4;
;           bf16x4 lo = *(const bf16x4*)vp, hi = *(const bf16x4*)(vp + 16);
	v_add_f32_e32 v123, v141, v130
	v_add_f32_e32 v103, v103, v137
	ds_bpermute_b32 v120, v97, v122
	ds_bpermute_b32 v121, v132, v123
	ds_bpermute_b32 v142, v97, v103
	v_add_f32_e32 v99, v99, v138
	v_add_f32_e32 v124, v80, v99
	ds_bpermute_b32 v126, v97, v124
	s_waitcnt lgkmcnt(2)
	v_pk_add_f32 v[128:129], v[122:123], v[120:121]
	ds_bpermute_b32 v80, v132, v128
	s_waitcnt lgkmcnt(2)
	v_add_f32_e32 v125, v103, v142
	ds_bpermute_b32 v127, v132, v125
	v_cndmask_b32_e64 v97, 0, v130, s[8:9]
	v_add_f32_e32 v123, v130, v121
	s_waitcnt lgkmcnt(1)
	v_add_f32_e32 v101, v120, v80
	v_cndmask_b32_e64 v120, 0, v120, s[8:9]
	v_cndmask_b32_e64 v120, v120, v80, s[6:7]
	s_waitcnt lgkmcnt(0)
	v_pk_add_f32 v[130:131], v[124:125], v[126:127]
	v_cndmask_b32_e64 v101, v120, v101, s[4:5]
	ds_bpermute_b32 v120, v132, v130
	v_cndmask_b32_e64 v97, v97, v121, s[6:7]
	v_cndmask_b32_e64 v123, v97, v123, s[4:5]
	v_cndmask_b32_e64 v97, 0, v126, s[8:9]
	v_cndmask_b32_e64 v143, 0, v142, s[8:9]
	v_pk_add_f32 v[128:129], v[128:129], v[80:81]
	s_waitcnt lgkmcnt(0)
	v_add_f32_e32 v80, v126, v120
	v_cndmask_b32_e64 v97, v97, v120, s[6:7]
	v_pk_add_f32 v[132:133], v[128:129], v[128:129] op_sel:[0,1] op_sel_hi:[1,0]
	v_cndmask_b32_e64 v97, v97, v80, s[4:5]
	v_add_f32_e32 v80, v142, v127
	v_cndmask_b32_e64 v121, v143, v127, s[6:7]
	v_cndmask_b32_e64 v125, v121, v80, s[4:5]
	v_mov_b32_e32 v121, v132
	v_pk_add_f32 v[120:121], v[130:131], v[120:121]
	v_add_f32_e32 v80, v76, v124
	v_add_f32_e32 v99, v77, v99
	v_mov_b32_e32 v76, v79
	v_mov_b32_e32 v77, v121
	v_pk_add_f32 v[76:77], v[76:77], v[96:97]
	v_add_f32_e32 v78, v78, v138
	v_add_f32_e32 v79, v80, v77
	v_add_f32_e32 v80, v99, v77
	v_add_f32_e32 v79, v113, v79
	v_add_f32_e32 v80, v113, v80
	v_mul_f32_e32 v79, 0x3fb8aa3b, v79
	v_mul_f32_e32 v80, 0x3fb8aa3b, v80
	v_exp_f32_e32 v79, v79
	v_exp_f32_e32 v80, v80
	v_mov_b32_e32 v124, v75
	v_mov_b32_e32 v99, v132
	v_add_f32_e32 v78, v78, v77
	v_add_f32_e32 v76, v76, v77
	v_cndmask_b32_e32 v77, 0, v79, vcc
	v_cndmask_b32_e64 v79, 0, v80, s[12:13]
	v_add_f32_e32 v80, v72, v103
	v_add_f32_e32 v96, v73, v137
	v_pk_add_f32 v[72:73], v[124:125], v[98:99]
	v_add_f32_e32 v74, v74, v136
	v_add_f32_e32 v75, v80, v73
	v_add_f32_e32 v80, v96, v73
	v_add_f32_e32 v75, v113, v75
	v_add_f32_e32 v80, v113, v80
	v_mul_f32_e32 v75, 0x3fb8aa3b, v75
	v_mul_f32_e32 v80, 0x3fb8aa3b, v80
	v_exp_f32_e32 v75, v75
	v_exp_f32_e32 v80, v80
	v_mov_b32_e32 v128, v71
	v_add_f32_e32 v74, v74, v73
	v_add_f32_e32 v72, v72, v73
	v_cndmask_b32_e64 v73, 0, v75, s[18:19]
	v_cndmask_b32_e64 v75, 0, v80, s[20:21]
	v_add_f32_e32 v80, v68, v122
	v_add_f32_e32 v96, v69, v135
	v_pk_add_f32 v[68:69], v[128:129], v[100:101]
	v_add_f32_e32 v70, v70, v134
	v_add_f32_e32 v71, v80, v69
	v_add_f32_e32 v80, v96, v69
	v_add_f32_e32 v68, v68, v69
	v_add_f32_e32 v71, v113, v71
	v_add_f32_e32 v80, v113, v80
	v_add_f32_e32 v68, v113, v68
	v_mul_f32_e32 v71, 0x3fb8aa3b, v71
	v_mul_f32_e32 v80, 0x3fb8aa3b, v80
	v_mul_f32_e32 v68, 0x3fb8aa3b, v68
	v_exp_f32_e32 v71, v71
	v_exp_f32_e32 v80, v80
	v_exp_f32_e32 v68, v68
	v_mov_b32_e32 v122, v67
	v_mov_b32_e32 v103, v81
	v_add_f32_e32 v70, v70, v69
	v_cndmask_b32_e64 v69, 0, v71, s[26:27]
	v_cndmask_b32_e64 v71, 0, v80, s[28:29]
	v_cndmask_b32_e64 v80, 0, v68, s[34:35]
	v_add_f32_e32 v68, v64, v141
	v_add_f32_e32 v96, v65, v140
	v_add_f32_e32 v66, v66, v139
	v_pk_add_f32 v[64:65], v[122:123], v[102:103]
	v_add_f32_e32 v78, v113, v78
	v_add_f32_e32 v67, v68, v65
	v_add_f32_e32 v68, v96, v65
	v_add_f32_e32 v66, v66, v65
	v_add_f32_e32 v64, v64, v65
	v_add_f32_e32 v76, v113, v76
	v_add_f32_e32 v74, v113, v74
	v_add_f32_e32 v72, v113, v72
	v_add_f32_e32 v70, v113, v70
	v_add_f32_e32 v67, v113, v67
	v_add_f32_e32 v68, v113, v68
	v_add_f32_e32 v66, v113, v66
	v_add_f32_e32 v64, v113, v64
	v_mul_f32_e32 v78, 0x3fb8aa3b, v78
	v_mul_f32_e32 v76, 0x3fb8aa3b, v76
	v_mul_f32_e32 v74, 0x3fb8aa3b, v74
	v_mul_f32_e32 v72, 0x3fb8aa3b, v72
	v_mul_f32_e32 v70, 0x3fb8aa3b, v70
	v_mul_f32_e32 v67, 0x3fb8aa3b, v67
	v_mul_f32_e32 v68, 0x3fb8aa3b, v68
	v_mul_f32_e32 v66, 0x3fb8aa3b, v66
	v_mul_f32_e32 v64, 0x3fb8aa3b, v64
	v_exp_f32_e32 v78, v78
	v_exp_f32_e32 v76, v76
	v_exp_f32_e32 v74, v74
	v_exp_f32_e32 v72, v72
	v_exp_f32_e32 v70, v70
	v_exp_f32_e32 v67, v67
	v_exp_f32_e32 v68, v68
	v_exp_f32_e32 v66, v66
	v_exp_f32_e32 v64, v64
	v_cndmask_b32_e64 v78, 0, v78, s[14:15]
	v_cndmask_b32_e64 v76, 0, v76, s[16:17]
	v_cndmask_b32_e64 v74, 0, v74, s[22:23]
	v_cndmask_b32_e64 v72, 0, v72, s[24:25]
	v_cndmask_b32_e64 v70, 0, v70, s[30:31]
	v_cndmask_b32_e64 v96, 0, v67, s[36:37]
	v_cndmask_b32_e64 v97, 0, v68, s[38:39]
	v_cndmask_b32_e64 v98, 0, v66, s[40:41]
	v_cndmask_b32_e64 v99, 0, v64, s[42:43]
	v_add_f32_e32 v100, v120, v121
	v_cvt_pk_bf16_f32 v64, v77, v79
	v_cvt_pk_bf16_f32 v65, v78, v76
	v_cvt_pk_bf16_f32 v66, v73, v75
	v_cvt_pk_bf16_f32 v67, v74, v72
	v_cvt_pk_bf16_f32 v68, v69, v71
	v_cvt_pk_bf16_f32 v69, v70, v80
	v_cvt_pk_bf16_f32 v70, v96, v97
	v_cvt_pk_bf16_f32 v71, v98, v99
	s_setprio 1
	v_add_u32_e32 v76, 0x4000, v119
	ds_read2_b64 v[72:75], v76 offset0:128 offset1:132
	v_add_u32_e32 v77, 0x4800, v119
	v_add_f32_e32 v113, v113, v100
	s_waitcnt lgkmcnt(0)
; __device__ void attn_item(const Params& p, int item, u16* O) {
;     ...
;       __builtin_amdgcn_s_setprio(1);
; #pragma unroll
;       for (int df = 0; df < 8; ++df)
; #pragma unroll
;         for (int kp = 0; kp < 2; ++kp) {
;           const u16* vp = Vt + (df * 16 + fr) * 72 + kp * 32 + g4 * 4;
;           bf16x4 lo = *(const bf16x4*)vp, hi = *(const bf16x4*)(vp + 16);
;           bf16x8 a = {lo[0], lo[1], lo[2], lo[3], hi[0], hi[1], hi[2], hi[3]};
;           o[df] = __builtin_amdgcn_mfma_f32_16x16x32_bf16(a, pb[kp], o[df], 0, 0, 0);
;         }
;       __builtin_amdgcn_s_setprio(0);
	v_mfma_f32_16x16x32_bf16 v[44:47], v[72:75], v[64:67], v[44:47]
	ds_read2_b64 v[72:75], v77 offset0:160 offset1:164
	s_waitcnt lgkmcnt(0)
	v_mfma_f32_16x16x32_bf16 v[60:63], v[72:75], v[64:67], v[60:63]
	ds_read2_b64 v[72:75], v76 offset0:136 offset1:140
	v_add_u32_e32 v76, 0x5000, v119
	s_waitcnt lgkmcnt(0)
	v_mfma_f32_16x16x32_bf16 v[44:47], v[72:75], v[68:71], v[44:47]
	ds_read2_b64 v[72:75], v77 offset0:168 offset1:172
	s_waitcnt lgkmcnt(0)
	v_mfma_f32_16x16x32_bf16 v[60:63], v[72:75], v[68:71], v[60:63]
	ds_read2_b64 v[72:75], v76 offset0:192 offset1:196
	s_waitcnt lgkmcnt(0)
	v_mfma_f32_16x16x32_bf16 v[56:59], v[72:75], v[64:67], v[56:59]
	ds_read2_b64 v[72:75], v76 offset0:200 offset1:204
	v_add_u32_e32 v76, 0x5800, v119
	s_waitcnt lgkmcnt(0)
	v_mfma_f32_16x16x32_bf16 v[56:59], v[72:75], v[68:71], v[56:59]
	ds_read2_b64 v[72:75], v76 offset0:224 offset1:228
	s_waitcnt lgkmcnt(0)
	v_mfma_f32_16x16x32_bf16 v[52:55], v[72:75], v[64:67], v[52:55]
	ds_read2_b64 v[72:75], v76 offset0:232 offset1:236
	v_add_u32_e32 v76, 0x6800, v119
	s_waitcnt lgkmcnt(0)
	v_mfma_f32_16x16x32_bf16 v[52:55], v[72:75], v[68:71], v[52:55]
	ds_read2_b64 v[72:75], v76 offset1:4
	s_waitcnt lgkmcnt(0)
	v_mfma_f32_16x16x32_bf16 v[48:51], v[72:75], v[64:67], v[48:51]
	ds_read2_b64 v[72:75], v76 offset0:8 offset1:12
	v_add_u32_e32 v76, 0x7000, v119
	s_waitcnt lgkmcnt(0)
	v_mfma_f32_16x16x32_bf16 v[48:51], v[72:75], v[68:71], v[48:51]
	ds_read2_b64 v[72:75], v76 offset0:32 offset1:36
	s_waitcnt lgkmcnt(0)
	v_mfma_f32_16x16x32_bf16 v[40:43], v[72:75], v[64:67], v[40:43]
	ds_read2_b64 v[72:75], v76 offset0:40 offset1:44
	v_add_u32_e32 v76, 0x7800, v119
	s_waitcnt lgkmcnt(0)
	v_mfma_f32_16x16x32_bf16 v[40:43], v[72:75], v[68:71], v[40:43]
	ds_read2_b64 v[72:75], v76 offset0:64 offset1:68
	s_waitcnt lgkmcnt(0)
	v_mfma_f32_16x16x32_bf16 v[32:35], v[72:75], v[64:67], v[32:35]
	ds_read2_b64 v[72:75], v76 offset0:72 offset1:76
	v_add_u32_e32 v76, 0x8000, v119
	s_waitcnt lgkmcnt(0)
	v_mfma_f32_16x16x32_bf16 v[32:35], v[72:75], v[68:71], v[32:35]
	ds_read2_b64 v[72:75], v76 offset0:96 offset1:100
	s_waitcnt lgkmcnt(0)
	v_mfma_f32_16x16x32_bf16 v[28:31], v[72:75], v[64:67], v[28:31]
	ds_read2_b64 v[64:67], v76 offset0:104 offset1:108
	s_waitcnt lgkmcnt(0)
	v_mfma_f32_16x16x32_bf16 v[28:31], v[64:67], v[68:71], v[28:31]
	s_setprio 0
